# S5 pass-2 entry state: all seven segment pairs loaded up front, recurrence unrolled
# speedup vs baseline: 1.0261x; 1.0034x over previous
.LBB0_396:
	global_load_dword v92, v[74:75], off offset:-256
	global_load_dword v93, v[74:75], off offset:0
	global_load_dword v94, v[74:75], off offset:256
	global_load_dword v95, v[74:75], off offset:512
	global_load_dword v96, v[74:75], off offset:768
	global_load_dword v97, v[74:75], off offset:1024
	global_load_dword v98, v[74:75], off offset:1280
	global_load_dword v99, v[74:75], off offset:1536
	global_load_dword v100, v[74:75], off offset:1792
	global_load_dword v101, v[74:75], off offset:2048
	global_load_dword v102, v[74:75], off offset:2304
	global_load_dword v103, v[74:75], off offset:2560
	global_load_dword v104, v[74:75], off offset:2816
	global_load_dword v105, v[74:75], off offset:3072
	v_pk_mul_f32 v[86:87], v[62:63], v[72:73] op_sel:[0,1] op_sel_hi:[1,0]
	s_add_i32 s20, s20, -1
	v_pk_fma_f32 v[88:89], v[60:61], v[72:73], v[86:87] neg_lo:[0,0,1] neg_hi:[0,0,1]
	v_pk_fma_f32 v[72:73], v[60:61], v[72:73], v[86:87]
	v_lshl_add_u64 v[74:75], v[74:75], 0, s[4:5]
	v_mov_b32_e32 v89, v73
	s_cmp_eq_u32 s20, 0
	s_waitcnt vmcnt(0)
	v_pk_add_f32 v[72:73], v[92:93], v[88:89]
	s_cbranch_scc1 .Ls5x_0
	v_pk_mul_f32 v[86:87], v[62:63], v[72:73] op_sel:[0,1] op_sel_hi:[1,0]
	s_add_i32 s20, s20, -1
	v_pk_fma_f32 v[88:89], v[60:61], v[72:73], v[86:87] neg_lo:[0,0,1] neg_hi:[0,0,1]
	v_pk_fma_f32 v[72:73], v[60:61], v[72:73], v[86:87]
	v_lshl_add_u64 v[74:75], v[74:75], 0, s[4:5]
	v_mov_b32_e32 v89, v73
	s_cmp_eq_u32 s20, 0
	s_waitcnt vmcnt(0)
	v_pk_add_f32 v[72:73], v[94:95], v[88:89]
	s_cbranch_scc1 .Ls5x_0
	v_pk_mul_f32 v[86:87], v[62:63], v[72:73] op_sel:[0,1] op_sel_hi:[1,0]
	s_add_i32 s20, s20, -1
	v_pk_fma_f32 v[88:89], v[60:61], v[72:73], v[86:87] neg_lo:[0,0,1] neg_hi:[0,0,1]
	v_pk_fma_f32 v[72:73], v[60:61], v[72:73], v[86:87]
	v_lshl_add_u64 v[74:75], v[74:75], 0, s[4:5]
	v_mov_b32_e32 v89, v73
	s_cmp_eq_u32 s20, 0
	s_waitcnt vmcnt(0)
	v_pk_add_f32 v[72:73], v[96:97], v[88:89]
	s_cbranch_scc1 .Ls5x_0
	v_pk_mul_f32 v[86:87], v[62:63], v[72:73] op_sel:[0,1] op_sel_hi:[1,0]
	s_add_i32 s20, s20, -1
	v_pk_fma_f32 v[88:89], v[60:61], v[72:73], v[86:87] neg_lo:[0,0,1] neg_hi:[0,0,1]
	v_pk_fma_f32 v[72:73], v[60:61], v[72:73], v[86:87]
	v_lshl_add_u64 v[74:75], v[74:75], 0, s[4:5]
	v_mov_b32_e32 v89, v73
	s_cmp_eq_u32 s20, 0
	s_waitcnt vmcnt(0)
	v_pk_add_f32 v[72:73], v[98:99], v[88:89]
	s_cbranch_scc1 .Ls5x_0
	v_pk_mul_f32 v[86:87], v[62:63], v[72:73] op_sel:[0,1] op_sel_hi:[1,0]
	s_add_i32 s20, s20, -1
	v_pk_fma_f32 v[88:89], v[60:61], v[72:73], v[86:87] neg_lo:[0,0,1] neg_hi:[0,0,1]
	v_pk_fma_f32 v[72:73], v[60:61], v[72:73], v[86:87]
	v_lshl_add_u64 v[74:75], v[74:75], 0, s[4:5]
	v_mov_b32_e32 v89, v73
	s_cmp_eq_u32 s20, 0
	s_waitcnt vmcnt(0)
	v_pk_add_f32 v[72:73], v[100:101], v[88:89]
	s_cbranch_scc1 .Ls5x_0
	v_pk_mul_f32 v[86:87], v[62:63], v[72:73] op_sel:[0,1] op_sel_hi:[1,0]
	s_add_i32 s20, s20, -1
	v_pk_fma_f32 v[88:89], v[60:61], v[72:73], v[86:87] neg_lo:[0,0,1] neg_hi:[0,0,1]
	v_pk_fma_f32 v[72:73], v[60:61], v[72:73], v[86:87]
	v_lshl_add_u64 v[74:75], v[74:75], 0, s[4:5]
	v_mov_b32_e32 v89, v73
	s_cmp_eq_u32 s20, 0
	s_waitcnt vmcnt(0)
	v_pk_add_f32 v[72:73], v[102:103], v[88:89]
	s_cbranch_scc1 .Ls5x_0
	v_pk_mul_f32 v[86:87], v[62:63], v[72:73] op_sel:[0,1] op_sel_hi:[1,0]
	s_add_i32 s20, s20, -1
	v_pk_fma_f32 v[88:89], v[60:61], v[72:73], v[86:87] neg_lo:[0,0,1] neg_hi:[0,0,1]
	v_pk_fma_f32 v[72:73], v[60:61], v[72:73], v[86:87]
	v_lshl_add_u64 v[74:75], v[74:75], 0, s[4:5]
	v_mov_b32_e32 v89, v73
	s_cmp_eq_u32 s20, 0
	s_waitcnt vmcnt(0)
	v_pk_add_f32 v[72:73], v[104:105], v[88:89]
.Ls5x_0:
	v_mul_f32_e32 v60, v78, v1
	v_mul_f32_e32 v61, 0.15915494, v60
	v_rndne_f32_e32 v61, v61
	v_fmac_f32_e32 v60, 0xc0c90000, v61
	v_mul_f32_e32 v3, v79, v1
	v_fmac_f32_e32 v60, 0xbafdaa22, v61
	v_mul_f32_e32 v3, 0x3fb8aa3b, v3
	v_mul_f32_e32 v60, 0.15915494, v60
	v_exp_f32_e32 v3, v3
	v_cos_f32_e32 v61, v60
	v_sin_f32_e32 v62, v60
	v_readlane_b32 s6, v254, 51
	v_readlane_b32 s7, v254, 52
	v_mul_f32_e32 v60, v3, v61
	v_mul_f32_e32 v62, v3, v62
	v_mov_b32_e32 v74, 0
	v_mov_b32_e32 v61, v60
	v_mov_b32_e32 v63, v62
	v_lshl_add_u64 v[76:77], s[6:7], 0, v[58:59]
	s_mov_b32 s20, s53
	v_mov_b32_e32 v75, v74
.LBB0_398:
	global_load_dword v92, v[76:77], off offset:-256
	global_load_dword v93, v[76:77], off offset:0
	global_load_dword v94, v[76:77], off offset:256
	global_load_dword v95, v[76:77], off offset:512
	global_load_dword v96, v[76:77], off offset:768
	global_load_dword v97, v[76:77], off offset:1024
	global_load_dword v98, v[76:77], off offset:1280
	global_load_dword v99, v[76:77], off offset:1536
	global_load_dword v100, v[76:77], off offset:1792
	global_load_dword v101, v[76:77], off offset:2048
	global_load_dword v102, v[76:77], off offset:2304
	global_load_dword v103, v[76:77], off offset:2560
	global_load_dword v104, v[76:77], off offset:2816
	global_load_dword v105, v[76:77], off offset:3072
	v_pk_mul_f32 v[86:87], v[62:63], v[74:75] op_sel:[0,1] op_sel_hi:[1,0]
	s_add_i32 s20, s20, -1
	v_pk_fma_f32 v[88:89], v[60:61], v[74:75], v[86:87] neg_lo:[0,0,1] neg_hi:[0,0,1]
	v_pk_fma_f32 v[74:75], v[60:61], v[74:75], v[86:87]
	v_lshl_add_u64 v[76:77], v[76:77], 0, s[4:5]
	v_mov_b32_e32 v89, v75
	s_cmp_lg_u32 s20, 0
	s_waitcnt vmcnt(0)
	v_pk_add_f32 v[74:75], v[92:93], v[88:89]
	s_cbranch_scc0 .Ls5x_1
	v_pk_mul_f32 v[86:87], v[62:63], v[74:75] op_sel:[0,1] op_sel_hi:[1,0]
	s_add_i32 s20, s20, -1
	v_pk_fma_f32 v[88:89], v[60:61], v[74:75], v[86:87] neg_lo:[0,0,1] neg_hi:[0,0,1]
	v_pk_fma_f32 v[74:75], v[60:61], v[74:75], v[86:87]
	v_lshl_add_u64 v[76:77], v[76:77], 0, s[4:5]
	v_mov_b32_e32 v89, v75
	s_cmp_lg_u32 s20, 0
	s_waitcnt vmcnt(0)
	v_pk_add_f32 v[74:75], v[94:95], v[88:89]
	s_cbranch_scc0 .Ls5x_1
	v_pk_mul_f32 v[86:87], v[62:63], v[74:75] op_sel:[0,1] op_sel_hi:[1,0]
	s_add_i32 s20, s20, -1
	v_pk_fma_f32 v[88:89], v[60:61], v[74:75], v[86:87] neg_lo:[0,0,1] neg_hi:[0,0,1]
	v_pk_fma_f32 v[74:75], v[60:61], v[74:75], v[86:87]
	v_lshl_add_u64 v[76:77], v[76:77], 0, s[4:5]
	v_mov_b32_e32 v89, v75
	s_cmp_lg_u32 s20, 0
	s_waitcnt vmcnt(0)
	v_pk_add_f32 v[74:75], v[96:97], v[88:89]
	s_cbranch_scc0 .Ls5x_1
	v_pk_mul_f32 v[86:87], v[62:63], v[74:75] op_sel:[0,1] op_sel_hi:[1,0]
	s_add_i32 s20, s20, -1
	v_pk_fma_f32 v[88:89], v[60:61], v[74:75], v[86:87] neg_lo:[0,0,1] neg_hi:[0,0,1]
	v_pk_fma_f32 v[74:75], v[60:61], v[74:75], v[86:87]
	v_lshl_add_u64 v[76:77], v[76:77], 0, s[4:5]
	v_mov_b32_e32 v89, v75
	s_cmp_lg_u32 s20, 0
	s_waitcnt vmcnt(0)
	v_pk_add_f32 v[74:75], v[98:99], v[88:89]
	s_cbranch_scc0 .Ls5x_1
	v_pk_mul_f32 v[86:87], v[62:63], v[74:75] op_sel:[0,1] op_sel_hi:[1,0]
	s_add_i32 s20, s20, -1
	v_pk_fma_f32 v[88:89], v[60:61], v[74:75], v[86:87] neg_lo:[0,0,1] neg_hi:[0,0,1]
	v_pk_fma_f32 v[74:75], v[60:61], v[74:75], v[86:87]
	v_lshl_add_u64 v[76:77], v[76:77], 0, s[4:5]
	v_mov_b32_e32 v89, v75
	s_cmp_lg_u32 s20, 0
	s_waitcnt vmcnt(0)
	v_pk_add_f32 v[74:75], v[100:101], v[88:89]
	s_cbranch_scc0 .Ls5x_1
	v_pk_mul_f32 v[86:87], v[62:63], v[74:75] op_sel:[0,1] op_sel_hi:[1,0]
	s_add_i32 s20, s20, -1
	v_pk_fma_f32 v[88:89], v[60:61], v[74:75], v[86:87] neg_lo:[0,0,1] neg_hi:[0,0,1]
	v_pk_fma_f32 v[74:75], v[60:61], v[74:75], v[86:87]
	v_lshl_add_u64 v[76:77], v[76:77], 0, s[4:5]
	v_mov_b32_e32 v89, v75
	s_cmp_lg_u32 s20, 0
	s_waitcnt vmcnt(0)
	v_pk_add_f32 v[74:75], v[102:103], v[88:89]
	s_cbranch_scc0 .Ls5x_1
	v_pk_mul_f32 v[86:87], v[62:63], v[74:75] op_sel:[0,1] op_sel_hi:[1,0]
	s_add_i32 s20, s20, -1
	v_pk_fma_f32 v[88:89], v[60:61], v[74:75], v[86:87] neg_lo:[0,0,1] neg_hi:[0,0,1]
	v_pk_fma_f32 v[74:75], v[60:61], v[74:75], v[86:87]
	v_lshl_add_u64 v[76:77], v[76:77], 0, s[4:5]
	v_mov_b32_e32 v89, v75
	s_cmp_lg_u32 s20, 0
	s_waitcnt vmcnt(0)
	v_pk_add_f32 v[74:75], v[104:105], v[88:89]
.Ls5x_1:
	v_mul_f32_e32 v60, v80, v1
	v_mul_f32_e32 v61, 0.15915494, v60
	v_rndne_f32_e32 v61, v61
	v_fmac_f32_e32 v60, 0xc0c90000, v61
	v_mul_f32_e32 v3, v82, v1
	v_fmac_f32_e32 v60, 0xbafdaa22, v61
	v_mul_f32_e32 v3, 0x3fb8aa3b, v3
	v_mul_f32_e32 v60, 0.15915494, v60
	v_exp_f32_e32 v3, v3
	v_cos_f32_e32 v61, v60
	v_sin_f32_e32 v62, v60
	v_readlane_b32 s6, v254, 53
	v_readlane_b32 s7, v254, 54
	v_mul_f32_e32 v60, v3, v61
	v_mul_f32_e32 v62, v3, v62
	v_mov_b32_e32 v76, 0
	v_mov_b32_e32 v61, v60
	v_mov_b32_e32 v63, v62
	v_lshl_add_u64 v[78:79], s[6:7], 0, v[58:59]
	s_mov_b32 s20, s53
	v_mov_b32_e32 v77, v76
.LBB0_400:
	global_load_dword v92, v[78:79], off offset:-256
	global_load_dword v93, v[78:79], off offset:0
	global_load_dword v94, v[78:79], off offset:256
	global_load_dword v95, v[78:79], off offset:512
	global_load_dword v96, v[78:79], off offset:768
	global_load_dword v97, v[78:79], off offset:1024
	global_load_dword v98, v[78:79], off offset:1280
	global_load_dword v99, v[78:79], off offset:1536
	global_load_dword v100, v[78:79], off offset:1792
	global_load_dword v101, v[78:79], off offset:2048
	global_load_dword v102, v[78:79], off offset:2304
	global_load_dword v103, v[78:79], off offset:2560
	global_load_dword v104, v[78:79], off offset:2816
	global_load_dword v105, v[78:79], off offset:3072
	v_pk_mul_f32 v[88:89], v[62:63], v[76:77] op_sel:[0,1] op_sel_hi:[1,0]
	s_add_i32 s20, s20, -1
	v_pk_fma_f32 v[90:91], v[60:61], v[76:77], v[88:89] neg_lo:[0,0,1] neg_hi:[0,0,1]
	v_pk_fma_f32 v[76:77], v[60:61], v[76:77], v[88:89]
	v_lshl_add_u64 v[78:79], v[78:79], 0, s[4:5]
	v_mov_b32_e32 v91, v77
	s_cmp_lg_u32 s20, 0
	s_waitcnt vmcnt(0)
	v_pk_add_f32 v[76:77], v[92:93], v[90:91]
	s_cbranch_scc0 .Ls5x_2
	v_pk_mul_f32 v[88:89], v[62:63], v[76:77] op_sel:[0,1] op_sel_hi:[1,0]
	s_add_i32 s20, s20, -1
	v_pk_fma_f32 v[90:91], v[60:61], v[76:77], v[88:89] neg_lo:[0,0,1] neg_hi:[0,0,1]
	v_pk_fma_f32 v[76:77], v[60:61], v[76:77], v[88:89]
	v_lshl_add_u64 v[78:79], v[78:79], 0, s[4:5]
	v_mov_b32_e32 v91, v77
	s_cmp_lg_u32 s20, 0
	s_waitcnt vmcnt(0)
	v_pk_add_f32 v[76:77], v[94:95], v[90:91]
	s_cbranch_scc0 .Ls5x_2
	v_pk_mul_f32 v[88:89], v[62:63], v[76:77] op_sel:[0,1] op_sel_hi:[1,0]
	s_add_i32 s20, s20, -1
	v_pk_fma_f32 v[90:91], v[60:61], v[76:77], v[88:89] neg_lo:[0,0,1] neg_hi:[0,0,1]
	v_pk_fma_f32 v[76:77], v[60:61], v[76:77], v[88:89]
	v_lshl_add_u64 v[78:79], v[78:79], 0, s[4:5]
	v_mov_b32_e32 v91, v77
	s_cmp_lg_u32 s20, 0
	s_waitcnt vmcnt(0)
	v_pk_add_f32 v[76:77], v[96:97], v[90:91]
	s_cbranch_scc0 .Ls5x_2
	v_pk_mul_f32 v[88:89], v[62:63], v[76:77] op_sel:[0,1] op_sel_hi:[1,0]
	s_add_i32 s20, s20, -1
	v_pk_fma_f32 v[90:91], v[60:61], v[76:77], v[88:89] neg_lo:[0,0,1] neg_hi:[0,0,1]
	v_pk_fma_f32 v[76:77], v[60:61], v[76:77], v[88:89]
	v_lshl_add_u64 v[78:79], v[78:79], 0, s[4:5]
	v_mov_b32_e32 v91, v77
	s_cmp_lg_u32 s20, 0
	s_waitcnt vmcnt(0)
	v_pk_add_f32 v[76:77], v[98:99], v[90:91]
	s_cbranch_scc0 .Ls5x_2
	v_pk_mul_f32 v[88:89], v[62:63], v[76:77] op_sel:[0,1] op_sel_hi:[1,0]
	s_add_i32 s20, s20, -1
	v_pk_fma_f32 v[90:91], v[60:61], v[76:77], v[88:89] neg_lo:[0,0,1] neg_hi:[0,0,1]
	v_pk_fma_f32 v[76:77], v[60:61], v[76:77], v[88:89]
	v_lshl_add_u64 v[78:79], v[78:79], 0, s[4:5]
	v_mov_b32_e32 v91, v77
	s_cmp_lg_u32 s20, 0
	s_waitcnt vmcnt(0)
	v_pk_add_f32 v[76:77], v[100:101], v[90:91]
	s_cbranch_scc0 .Ls5x_2
	v_pk_mul_f32 v[88:89], v[62:63], v[76:77] op_sel:[0,1] op_sel_hi:[1,0]
	s_add_i32 s20, s20, -1
	v_pk_fma_f32 v[90:91], v[60:61], v[76:77], v[88:89] neg_lo:[0,0,1] neg_hi:[0,0,1]
	v_pk_fma_f32 v[76:77], v[60:61], v[76:77], v[88:89]
	v_lshl_add_u64 v[78:79], v[78:79], 0, s[4:5]
	v_mov_b32_e32 v91, v77
	s_cmp_lg_u32 s20, 0
	s_waitcnt vmcnt(0)
	v_pk_add_f32 v[76:77], v[102:103], v[90:91]
	s_cbranch_scc0 .Ls5x_2
	v_pk_mul_f32 v[88:89], v[62:63], v[76:77] op_sel:[0,1] op_sel_hi:[1,0]
	s_add_i32 s20, s20, -1
	v_pk_fma_f32 v[90:91], v[60:61], v[76:77], v[88:89] neg_lo:[0,0,1] neg_hi:[0,0,1]
	v_pk_fma_f32 v[76:77], v[60:61], v[76:77], v[88:89]
	v_lshl_add_u64 v[78:79], v[78:79], 0, s[4:5]
	v_mov_b32_e32 v91, v77
	s_cmp_lg_u32 s20, 0
	s_waitcnt vmcnt(0)
	v_pk_add_f32 v[76:77], v[104:105], v[90:91]
.Ls5x_2:
	v_mul_f32_e32 v3, v84, v1
	v_mul_f32_e32 v1, v83, v1
	v_mul_f32_e32 v60, 0.15915494, v1
	v_rndne_f32_e32 v60, v60
	v_fmac_f32_e32 v1, 0xc0c90000, v60
	v_fmac_f32_e32 v1, 0xbafdaa22, v60
	v_mul_f32_e32 v3, 0x3fb8aa3b, v3
	v_mul_f32_e32 v1, 0.15915494, v1
	v_exp_f32_e32 v3, v3
	v_cos_f32_e32 v60, v1
	v_sin_f32_e32 v1, v1
	v_readlane_b32 s6, v254, 55
	v_readlane_b32 s7, v254, 56
	v_mul_f32_e32 v60, v3, v60
	v_mul_f32_e32 v62, v3, v1
	v_mov_b32_e32 v90, 0
	v_mov_b32_e32 v61, v60
	v_mov_b32_e32 v63, v62
	v_lshl_add_u64 v[58:59], s[6:7], 0, v[58:59]
	s_mov_b32 s20, s53
	v_mov_b32_e32 v91, v90
.LBB0_402:
	global_load_dword v92, v[58:59], off offset:-256
	global_load_dword v93, v[58:59], off offset:0
	global_load_dword v94, v[58:59], off offset:256
	global_load_dword v95, v[58:59], off offset:512
	global_load_dword v96, v[58:59], off offset:768
	global_load_dword v97, v[58:59], off offset:1024
	global_load_dword v98, v[58:59], off offset:1280
	global_load_dword v99, v[58:59], off offset:1536
	global_load_dword v100, v[58:59], off offset:1792
	global_load_dword v101, v[58:59], off offset:2048
	global_load_dword v102, v[58:59], off offset:2304
	global_load_dword v103, v[58:59], off offset:2560
	global_load_dword v104, v[58:59], off offset:2816
	global_load_dword v105, v[58:59], off offset:3072
	v_pk_mul_f32 v[82:83], v[62:63], v[90:91] op_sel:[0,1] op_sel_hi:[1,0]
	s_add_i32 s20, s20, -1
	v_pk_fma_f32 v[84:85], v[60:61], v[90:91], v[82:83] neg_lo:[0,0,1] neg_hi:[0,0,1]
	v_pk_fma_f32 v[82:83], v[60:61], v[90:91], v[82:83]
	v_lshl_add_u64 v[58:59], v[58:59], 0, s[4:5]
	v_mov_b32_e32 v85, v83
	s_cmp_eq_u32 s20, 0
	s_waitcnt vmcnt(0)
	v_pk_add_f32 v[90:91], v[92:93], v[84:85]
	s_cbranch_scc1 .Ls5x_3
	v_pk_mul_f32 v[82:83], v[62:63], v[90:91] op_sel:[0,1] op_sel_hi:[1,0]
	s_add_i32 s20, s20, -1
	v_pk_fma_f32 v[84:85], v[60:61], v[90:91], v[82:83] neg_lo:[0,0,1] neg_hi:[0,0,1]
	v_pk_fma_f32 v[82:83], v[60:61], v[90:91], v[82:83]
	v_lshl_add_u64 v[58:59], v[58:59], 0, s[4:5]
	v_mov_b32_e32 v85, v83
	s_cmp_eq_u32 s20, 0
	s_waitcnt vmcnt(0)
	v_pk_add_f32 v[90:91], v[94:95], v[84:85]
	s_cbranch_scc1 .Ls5x_3
	v_pk_mul_f32 v[82:83], v[62:63], v[90:91] op_sel:[0,1] op_sel_hi:[1,0]
	s_add_i32 s20, s20, -1
	v_pk_fma_f32 v[84:85], v[60:61], v[90:91], v[82:83] neg_lo:[0,0,1] neg_hi:[0,0,1]
	v_pk_fma_f32 v[82:83], v[60:61], v[90:91], v[82:83]
	v_lshl_add_u64 v[58:59], v[58:59], 0, s[4:5]
	v_mov_b32_e32 v85, v83
	s_cmp_eq_u32 s20, 0
	s_waitcnt vmcnt(0)
	v_pk_add_f32 v[90:91], v[96:97], v[84:85]
	s_cbranch_scc1 .Ls5x_3
	v_pk_mul_f32 v[82:83], v[62:63], v[90:91] op_sel:[0,1] op_sel_hi:[1,0]
	s_add_i32 s20, s20, -1
	v_pk_fma_f32 v[84:85], v[60:61], v[90:91], v[82:83] neg_lo:[0,0,1] neg_hi:[0,0,1]
	v_pk_fma_f32 v[82:83], v[60:61], v[90:91], v[82:83]
	v_lshl_add_u64 v[58:59], v[58:59], 0, s[4:5]
	v_mov_b32_e32 v85, v83
	s_cmp_eq_u32 s20, 0
	s_waitcnt vmcnt(0)
	v_pk_add_f32 v[90:91], v[98:99], v[84:85]
	s_cbranch_scc1 .Ls5x_3
	v_pk_mul_f32 v[82:83], v[62:63], v[90:91] op_sel:[0,1] op_sel_hi:[1,0]
	s_add_i32 s20, s20, -1
	v_pk_fma_f32 v[84:85], v[60:61], v[90:91], v[82:83] neg_lo:[0,0,1] neg_hi:[0,0,1]
	v_pk_fma_f32 v[82:83], v[60:61], v[90:91], v[82:83]
	v_lshl_add_u64 v[58:59], v[58:59], 0, s[4:5]
	v_mov_b32_e32 v85, v83
	s_cmp_eq_u32 s20, 0
	s_waitcnt vmcnt(0)
	v_pk_add_f32 v[90:91], v[100:101], v[84:85]
	s_cbranch_scc1 .Ls5x_3
	v_pk_mul_f32 v[82:83], v[62:63], v[90:91] op_sel:[0,1] op_sel_hi:[1,0]
	s_add_i32 s20, s20, -1
	v_pk_fma_f32 v[84:85], v[60:61], v[90:91], v[82:83] neg_lo:[0,0,1] neg_hi:[0,0,1]
	v_pk_fma_f32 v[82:83], v[60:61], v[90:91], v[82:83]
	v_lshl_add_u64 v[58:59], v[58:59], 0, s[4:5]
	v_mov_b32_e32 v85, v83
	s_cmp_eq_u32 s20, 0
	s_waitcnt vmcnt(0)
	v_pk_add_f32 v[90:91], v[102:103], v[84:85]
	s_cbranch_scc1 .Ls5x_3
	v_pk_mul_f32 v[82:83], v[62:63], v[90:91] op_sel:[0,1] op_sel_hi:[1,0]
	s_add_i32 s20, s20, -1
	v_pk_fma_f32 v[84:85], v[60:61], v[90:91], v[82:83] neg_lo:[0,0,1] neg_hi:[0,0,1]
	v_pk_fma_f32 v[82:83], v[60:61], v[90:91], v[82:83]
	v_lshl_add_u64 v[58:59], v[58:59], 0, s[4:5]
	v_mov_b32_e32 v85, v83
	s_cmp_eq_u32 s20, 0
	s_waitcnt vmcnt(0)
	v_pk_add_f32 v[90:91], v[104:105], v[84:85]
.Ls5x_3:
	s_branch .LBB0_404
.LBB0_403:
	v_mov_b32_e32 v3, v2
	s_waitcnt vmcnt(0)
	v_mov_b64_e32 v[90:91], v[2:3]
	v_mov_b64_e32 v[76:77], v[2:3]
	v_mov_b64_e32 v[74:75], v[2:3]
	v_mov_b64_e32 v[72:73], v[2:3]
